# resid epilogue: warm-up loads touch all vector cache lines before the first wait so the serialized gate/cscale/norm loads hit L1
# speedup vs baseline: 1.0101x; 1.0045x over previous
.LBB0_1021:
	s_add_i32 vcc_hi, s46, 2
	s_add_u32 s84, s44, 0x80
	s_addc_u32 s47, s45, 0
	s_add_i32 s29, 0, 0x10000
	v_add_u32_e32 v96, s29, v225
	ds_read_b128 v[56:59], v96
	ds_read_b128 v[68:71], v96 offset:1024
	s_cmp_eq_u32 s90, s46
	s_cselect_b32 s46, s80, s84
	s_cselect_b32 s47, s81, s47
	s_cselect_b32 s85, s83, vcc_lo
	s_cselect_b32 s84, s82, s87
	s_add_i32 m0, s2, 0xc000
	ds_read_b128 v[102:105], v227
	ds_read_b128 v[112:115], v227 offset:1024
	ds_read_b128 v[124:127], v227 offset:2048
	ds_read_b128 v[192:195], v227 offset:3072
	ds_read_b128 v[196:199], v227 offset:4096
	ds_read_b128 v[200:203], v227 offset:5120
	global_load_lds_dwordx4 v188, s[44:45]
	s_add_i32 m0, s2, 0xe000
	s_mov_b64 exec, s[98:99]
	global_load_lds_dwordx4 v190, s[44:45]
	s_mov_b64 exec, -1
	s_waitcnt lgkmcnt(6)
	s_setprio 1
	s_barrier
	s_waitcnt lgkmcnt(0)
	v_mfma_f32_16x16x32_bf16 v[172:175], v[56:59], v[102:105], v[172:175]
	v_mfma_f32_16x16x32_bf16 v[168:171], v[80:83], v[102:105], v[168:171]
	v_mfma_f32_16x16x32_bf16 v[156:159], v[56:59], v[124:127], v[156:159]
	v_mfma_f32_16x16x32_bf16 v[152:155], v[80:83], v[124:127], v[152:155]
	v_mfma_f32_16x16x32_bf16 v[132:135], v[56:59], v[196:199], v[132:135]
	v_mfma_f32_16x16x32_bf16 v[128:131], v[80:83], v[196:199], v[128:131]
	v_mfma_f32_16x16x32_bf16 v[172:175], v[68:71], v[112:115], v[172:175]
	v_mfma_f32_16x16x32_bf16 v[168:171], v[98:101], v[112:115], v[168:171]
	v_mfma_f32_16x16x32_bf16 v[156:159], v[68:71], v[192:195], v[156:159]
	v_mfma_f32_16x16x32_bf16 v[152:155], v[98:101], v[192:195], v[152:155]
	v_mfma_f32_16x16x32_bf16 v[132:135], v[68:71], v[200:203], v[132:135]
	v_mfma_f32_16x16x32_bf16 v[128:131], v[98:101], v[200:203], v[128:131]
	s_barrier
	s_setprio 0
	s_add_i32 s96, 0, 0x14000
	s_add_i32 s29, s29, s18
	v_add_u32_e32 v96, s96, v225
	v_lshl_add_u64 v[106:107], s[84:85], 0, v[182:183]
	s_mov_b32 m0, s29
	ds_read_b128 v[228:231], v96
	ds_read_b128 v[232:235], v96 offset:1024
	ds_read_b128 v[236:239], v96 offset:2048
	ds_read_b128 v[240:243], v96 offset:3072
	global_load_lds_dwordx4 v182, s[84:85]
	v_lshl_add_u64 v[248:249], s[84:85], 0, v[186:187]
	s_add_i32 m0, s29, 0x2000
	s_nop 0
	global_load_lds_dwordx4 v186, s[84:85]
	s_setprio 1
	s_barrier
	s_waitcnt lgkmcnt(0)
	v_mfma_f32_16x16x32_bf16 v[164:167], v[228:231], v[102:105], v[164:167]
	v_mfma_f32_16x16x32_bf16 v[102:105], v[236:239], v[102:105], v[160:163]
	v_mfma_f32_16x16x32_bf16 v[120:123], v[228:231], v[196:199], v[120:123]
	s_mov_b32 m0, s2
	v_mfma_f32_16x16x32_bf16 v[116:119], v[236:239], v[196:199], v[116:119]
	v_lshl_add_u64 v[250:251], s[46:47], 0, v[176:177]
	v_mfma_f32_16x16x32_bf16 v[164:167], v[232:235], v[112:115], v[164:167]
	v_mfma_f32_16x16x32_bf16 v[102:105], v[240:243], v[112:115], v[102:105]
	v_mfma_f32_16x16x32_bf16 v[112:115], v[228:231], v[124:127], v[148:151]
	v_mfma_f32_16x16x32_bf16 v[124:127], v[236:239], v[124:127], v[144:147]
	v_mfma_f32_16x16x32_bf16 v[120:123], v[232:235], v[200:203], v[120:123]
	v_mfma_f32_16x16x32_bf16 v[116:119], v[240:243], v[200:203], v[116:119]
	v_mfma_f32_16x16x32_bf16 v[112:115], v[232:235], v[192:195], v[112:115]
	v_mfma_f32_16x16x32_bf16 v[124:127], v[240:243], v[192:195], v[124:127]
	s_barrier
	s_setprio 0
	ds_read_b128 v[144:147], v227 offset:16384
	ds_read_b128 v[148:151], v227 offset:17408
	ds_read_b128 v[160:163], v227 offset:18432
	ds_read_b128 v[192:195], v227 offset:19456
	ds_read_b128 v[196:199], v227 offset:20480
	ds_read_b128 v[200:203], v227 offset:21504
	global_load_lds_dwordx4 v176, s[46:47]
	v_lshl_add_u64 v[252:253], s[46:47], 0, v[184:185]
	s_mov_b32 m0, s3
	s_mov_b64 exec, s[98:99]
	global_load_lds_dwordx4 v184, s[46:47]
	s_mov_b64 exec, -1
	s_waitcnt vmcnt(10)
	s_setprio 1
	s_barrier
	s_waitcnt lgkmcnt(0)
	v_mfma_f32_16x16x32_bf16 v[88:91], v[56:59], v[144:147], v[88:91]
	v_mfma_f32_16x16x32_bf16 v[84:87], v[80:83], v[144:147], v[84:87]
	v_mfma_f32_16x16x32_bf16 v[52:55], v[56:59], v[160:163], v[52:55]
	v_mfma_f32_16x16x32_bf16 v[48:51], v[80:83], v[160:163], v[48:51]
	v_mfma_f32_16x16x32_bf16 v[28:31], v[56:59], v[196:199], v[28:31]
	v_mfma_f32_16x16x32_bf16 v[24:27], v[80:83], v[196:199], v[24:27]
	v_mfma_f32_16x16x32_bf16 v[88:91], v[68:71], v[148:151], v[88:91]
	v_mfma_f32_16x16x32_bf16 v[84:87], v[98:101], v[148:151], v[84:87]
	v_mfma_f32_16x16x32_bf16 v[52:55], v[68:71], v[192:195], v[52:55]
	v_mfma_f32_16x16x32_bf16 v[48:51], v[98:101], v[192:195], v[48:51]
	v_mfma_f32_16x16x32_bf16 v[28:31], v[68:71], v[200:203], v[28:31]
	v_mfma_f32_16x16x32_bf16 v[24:27], v[98:101], v[200:203], v[24:27]
	s_barrier
	s_setprio 0
	v_add_u32_e32 v96, 0x18000, v225
	ds_read_b128 v[80:83], v96 offset:2048
	ds_read_b128 v[98:101], v96 offset:3072
	s_add_u32 s84, s84, s57
	s_addc_u32 s85, s85, 0
	s_add_i32 s29, s96, s18
	v_lshl_add_u64 v[218:219], s[84:85], 0, v[182:183]
	s_mov_b32 m0, s29
	v_lshl_add_u64 v[220:221], s[84:85], 0, v[186:187]
	global_load_lds_dwordx4 v182, s[84:85]
	s_add_i32 m0, s29, 0x2000
	s_nop 0
	global_load_lds_dwordx4 v186, s[84:85]
	s_waitcnt vmcnt(6)
	s_setprio 1
	s_barrier
	v_mfma_f32_16x16x32_bf16 v[44:47], v[228:231], v[160:163], v[44:47]
	v_mfma_f32_16x16x32_bf16 v[40:43], v[236:239], v[160:163], v[40:43]
	v_mfma_f32_16x16x32_bf16 v[20:23], v[228:231], v[196:199], v[20:23]
	s_add_i32 s29, 0, 0x18000
	v_mfma_f32_16x16x32_bf16 v[16:19], v[236:239], v[196:199], v[16:19]
	v_add_u32_e32 v96, s29, v225
	v_mfma_f32_16x16x32_bf16 v[56:59], v[228:231], v[144:147], v[76:79]
	v_mfma_f32_16x16x32_bf16 v[68:71], v[236:239], v[144:147], v[72:75]
	v_mfma_f32_16x16x32_bf16 v[44:47], v[232:235], v[192:195], v[44:47]
	v_mfma_f32_16x16x32_bf16 v[40:43], v[240:243], v[192:195], v[40:43]
	v_mfma_f32_16x16x32_bf16 v[20:23], v[232:235], v[200:203], v[20:23]
	v_mfma_f32_16x16x32_bf16 v[16:19], v[240:243], v[200:203], v[16:19]
	v_mfma_f32_16x16x32_bf16 v[56:59], v[232:235], v[148:151], v[56:59]
	v_mfma_f32_16x16x32_bf16 v[68:71], v[240:243], v[148:151], v[68:71]
	s_barrier
	s_setprio 0
	ds_read_b128 v[72:75], v96
	ds_read_b128 v[76:79], v96 offset:1024
	s_add_u32 s46, s46, s64
	s_addc_u32 s47, s47, 0
	s_mov_b32 m0, s4
	ds_read_b128 v[144:147], v227 offset:32768
	ds_read_b128 v[148:151], v227 offset:33792
	ds_read_b128 v[192:195], v227 offset:34816
	ds_read_b128 v[196:199], v227 offset:35840
	ds_read_b128 v[200:203], v227 offset:36864
	ds_read_b128 v[228:231], v227 offset:37888
	global_load_lds_dwordx4 v176, s[46:47]
	s_mov_b32 m0, s5
	s_mov_b64 exec, s[98:99]
	global_load_lds_dwordx4 v184, s[46:47]
	s_mov_b64 exec, -1
	s_waitcnt lgkmcnt(6)
	s_setprio 1
	s_barrier
	s_waitcnt lgkmcnt(0)
	v_mfma_f32_16x16x32_bf16 v[160:163], v[72:75], v[144:147], v[172:175]
	v_mfma_f32_16x16x32_bf16 v[172:175], v[76:79], v[148:151], v[160:163]
	v_mfma_f32_16x16x32_bf16 v[160:163], v[80:83], v[144:147], v[168:171]
	v_mfma_f32_16x16x32_bf16 v[156:159], v[72:75], v[192:195], v[156:159]
	v_mfma_f32_16x16x32_bf16 v[152:155], v[80:83], v[192:195], v[152:155]
	v_mfma_f32_16x16x32_bf16 v[132:135], v[72:75], v[200:203], v[132:135]
	v_mfma_f32_16x16x32_bf16 v[128:131], v[80:83], v[200:203], v[128:131]
	v_mfma_f32_16x16x32_bf16 v[168:171], v[98:101], v[148:151], v[160:163]
	v_mfma_f32_16x16x32_bf16 v[156:159], v[76:79], v[196:199], v[156:159]
	v_mfma_f32_16x16x32_bf16 v[152:155], v[98:101], v[196:199], v[152:155]
	v_mfma_f32_16x16x32_bf16 v[132:135], v[76:79], v[228:231], v[132:135]
	v_mfma_f32_16x16x32_bf16 v[128:131], v[98:101], v[228:231], v[128:131]
	s_barrier
	s_setprio 0
	s_add_i32 s46, 0, 0x1c000
	s_add_i32 s29, s29, s18
	v_add_u32_e32 v96, s46, v225
	v_lshl_add_u64 v[106:107], v[106:107], 0, s[6:7]
	s_mov_b32 m0, s29
	ds_read_b128 v[232:235], v96
	ds_read_b128 v[236:239], v96 offset:1024
	ds_read_b128 v[240:243], v96 offset:2048
	ds_read_b128 v[244:247], v96 offset:3072
	global_load_lds_dwordx4 v[106:107], off
	v_lshl_add_u64 v[106:107], v[248:249], 0, s[6:7]
	s_add_i32 m0, s29, 0x2000
	s_nop 0
	global_load_lds_dwordx4 v[106:107], off
	s_setprio 1
	s_barrier
	s_waitcnt lgkmcnt(0)
	v_mfma_f32_16x16x32_bf16 v[160:163], v[232:235], v[144:147], v[164:167]
	v_mfma_f32_16x16x32_bf16 v[102:105], v[240:243], v[144:147], v[102:105]
	v_mfma_f32_16x16x32_bf16 v[164:167], v[236:239], v[148:151], v[160:163]
	s_mov_b32 m0, s88
	v_mfma_f32_16x16x32_bf16 v[160:163], v[244:247], v[148:151], v[102:105]
	v_lshl_add_u64 v[106:107], v[250:251], 0, s[6:7]
	v_mfma_f32_16x16x32_bf16 v[102:105], v[232:235], v[192:195], v[112:115]
	v_mfma_f32_16x16x32_bf16 v[148:151], v[236:239], v[196:199], v[102:105]
	v_mfma_f32_16x16x32_bf16 v[102:105], v[240:243], v[192:195], v[124:127]
	v_mfma_f32_16x16x32_bf16 v[144:147], v[244:247], v[196:199], v[102:105]
	v_mfma_f32_16x16x32_bf16 v[102:105], v[232:235], v[200:203], v[120:123]
	v_mfma_f32_16x16x32_bf16 v[120:123], v[236:239], v[228:231], v[102:105]
	v_mfma_f32_16x16x32_bf16 v[102:105], v[240:243], v[200:203], v[116:119]
	v_mfma_f32_16x16x32_bf16 v[116:119], v[244:247], v[228:231], v[102:105]
	s_barrier
	s_setprio 0
	s_nop 2
	ds_read_b128 v[102:105], v227 offset:49152
	ds_read_b128 v[112:115], v227 offset:50176
	ds_read_b128 v[124:127], v227 offset:51200
	ds_read_b128 v[192:195], v227 offset:52224
	ds_read_b128 v[196:199], v227 offset:53248
	ds_read_b128 v[200:203], v227 offset:54272
	global_load_lds_dwordx4 v[106:107], off
	v_lshl_add_u64 v[106:107], v[252:253], 0, s[6:7]
	s_mov_b32 m0, s89
	s_mov_b64 exec, s[98:99]
	global_load_lds_dwordx4 v[106:107], off
	s_mov_b64 exec, -1
	s_waitcnt vmcnt(10)
	s_setprio 1
	s_barrier
	s_waitcnt lgkmcnt(0)
	v_mfma_f32_16x16x32_bf16 v[88:91], v[72:75], v[102:105], v[88:91]
	v_mfma_f32_16x16x32_bf16 v[84:87], v[80:83], v[102:105], v[84:87]
	v_mfma_f32_16x16x32_bf16 v[52:55], v[72:75], v[124:127], v[52:55]
	v_mfma_f32_16x16x32_bf16 v[48:51], v[80:83], v[124:127], v[48:51]
	v_mfma_f32_16x16x32_bf16 v[28:31], v[72:75], v[196:199], v[28:31]
	v_mfma_f32_16x16x32_bf16 v[24:27], v[80:83], v[196:199], v[24:27]
	v_mfma_f32_16x16x32_bf16 v[88:91], v[76:79], v[112:115], v[88:91]
	v_mfma_f32_16x16x32_bf16 v[84:87], v[98:101], v[112:115], v[84:87]
	v_mfma_f32_16x16x32_bf16 v[52:55], v[76:79], v[192:195], v[52:55]
	v_mfma_f32_16x16x32_bf16 v[48:51], v[98:101], v[192:195], v[48:51]
	v_mfma_f32_16x16x32_bf16 v[28:31], v[76:79], v[200:203], v[28:31]
	v_mfma_f32_16x16x32_bf16 v[24:27], v[98:101], v[200:203], v[24:27]
	s_barrier
	s_setprio 0
	v_add_u32_e32 v96, 0x10000, v225
	ds_read_b128 v[80:83], v96 offset:2048
	ds_read_b128 v[98:101], v96 offset:3072
	s_add_i32 s29, s46, s18
	v_lshl_add_u64 v[72:73], v[218:219], 0, s[6:7]
	s_mov_b32 m0, s29
	s_nop 0
	global_load_lds_dwordx4 v[72:73], off
	v_lshl_add_u64 v[72:73], v[220:221], 0, s[6:7]
	s_add_i32 m0, s29, 0x2000
	s_nop 0
	global_load_lds_dwordx4 v[72:73], off
	s_waitcnt vmcnt(6)
	s_setprio 1
	s_barrier
	v_mfma_f32_16x16x32_bf16 v[56:59], v[232:235], v[102:105], v[56:59]
	v_mfma_f32_16x16x32_bf16 v[76:79], v[236:239], v[112:115], v[56:59]
	v_mfma_f32_16x16x32_bf16 v[56:59], v[240:243], v[102:105], v[68:71]
	s_add_u32 s44, s44, 0x100
	v_mfma_f32_16x16x32_bf16 v[44:47], v[232:235], v[124:127], v[44:47]
	s_addc_u32 s45, s45, 0
	v_mfma_f32_16x16x32_bf16 v[40:43], v[240:243], v[124:127], v[40:43]
	s_add_u32 s87, s87, 0x100
	v_mfma_f32_16x16x32_bf16 v[20:23], v[232:235], v[196:199], v[20:23]
	s_addc_u32 vcc_lo, vcc_lo, 0
	v_mfma_f32_16x16x32_bf16 v[16:19], v[240:243], v[196:199], v[16:19]
	s_cmp_ge_u32 vcc_hi, s37
	v_mfma_f32_16x16x32_bf16 v[72:75], v[244:247], v[112:115], v[56:59]
	s_mov_b32 s46, vcc_hi
	v_mfma_f32_16x16x32_bf16 v[44:47], v[236:239], v[192:195], v[44:47]
	v_mfma_f32_16x16x32_bf16 v[40:43], v[244:247], v[192:195], v[40:43]
	v_mfma_f32_16x16x32_bf16 v[20:23], v[236:239], v[200:203], v[20:23]
	v_mfma_f32_16x16x32_bf16 v[16:19], v[244:247], v[200:203], v[16:19]
	s_barrier
	s_setprio 0
	s_cbranch_scc0 .LBB0_1021
	s_waitcnt lgkmcnt(0)
	s_mul_i32 s44, s86, 0xc0
	s_add_i32 s44, s44, s19
	s_cmpk_lt_u32 s44, 0x2000
	v_or_b32_e32 v198, s44, v223
	s_cselect_b32 s44, 1, 2
	v_mov_b32_e32 v56, s44
	v_cmp_lt_i32_e32 vcc, s23, v198
	v_lshl_or_b32 v192, s72, 8, v226
	v_ashrrev_i32_e32 v193, 31, v192
	v_cndmask_b32_e32 v228, 0, v56, vcc
	v_mul_u32_u24_e32 v56, 0x1800, v228
	v_lshlrev_b32_e32 v96, 2, v56
	v_lshl_add_u64 v[56:57], s[70:71], 0, v[96:97]
	v_lshlrev_b64 v[68:69], 2, v[192:193]
	v_lshl_add_u64 v[124:125], v[56:57], 0, v[68:69]
	global_load_dwordx4 v[56:59], v[124:125], off
	s_andn2_b64 vcc, exec, s[76:77]
	s_cbranch_vccnz .Lrs_warm_skip
	v_lshl_add_u64 v[202:203], s[66:67], 0, v[96:97]
	v_lshl_add_u64 v[202:203], v[202:203], 0, v[68:69]
	v_lshl_add_u64 v[194:195], s[58:59], 0, v[68:69]
	global_load_dwordx4 v[230:233], v[124:125], off offset:512
	global_load_dwordx4 v[230:233], v[202:203], off
	global_load_dwordx4 v[230:233], v[194:195], off
	global_load_dwordx4 v[230:233], v[202:203], off offset:512
	global_load_dwordx4 v[230:233], v[194:195], off offset:512
.Lrs_warm_skip:
	v_cndmask_b32_e64 v70, 0, 1, s[78:79]
	v_cmp_ne_u32_e64 s[46:47], 1, v70
	s_andn2_b64 vcc, exec, s[78:79]
	v_lshl_add_u64 v[196:197], s[54:55], 0, v[68:69]
	s_cbranch_vccnz .LBB0_1024
	global_load_dwordx4 v[80:83], v[196:197], off
	global_load_dwordx4 v[230:233], v[196:197], off offset:512
	s_waitcnt vmcnt(0)
	v_pk_mul_f32 v[58:59], v[58:59], v[82:83]
	v_pk_mul_f32 v[56:57], v[56:57], v[80:81]
